# v77 with a longer pause between polls of the local arrival counter (s_sleep 12): less traffic on the counter line
# speedup vs baseline: 1.0024x; 1.0024x over previous
; __device__ __forceinline__ unsigned xb_ld(unsigned* p)              { return __hip_atomic_load(p, __ATOMIC_RELAXED, __HIP_MEMORY_SCOPE_AGENT); }
; #define XB_SPIN(cond, bar) do { unsigned _sp = 0; while (cond) { __builtin_amdgcn_s_sleep(1); \
;     if ((++_sp & 255u) == 0u) { if (xb_ld(&(bar)[XB_TMO])) break; if (_sp > XB_SPIN_CAP) { atomicAdd(&(bar)[XB_TMO], 1u); break; } } } } while (0)
; __device__ __forceinline__ void xcd_barrier(const XcdBarrier& b, bool leader) {
;     ...
;             XB_SPIN(xb_ld(&bar[XB_XGEN(b.x)]) == gen, bar);
.Lmy_spin_k1:
	s_sleep 12
	global_load_dword v2, v5, s[2:3] offset:128 sc1
	s_add_i32 s10, s10, 1
	s_cmp_gt_u32 s10, 0x100000
	s_cbranch_scc1 .Lmy_done_k1
	s_waitcnt vmcnt(0)
	v_sub_u32_e32 v2, v2, v4
	v_cmp_gt_i32_e32 vcc, 0, v2
	s_cbranch_vccnz .Lmy_spin_k1
